# all three GEMM K-loops (in-proj, out-proj x2): LDS-DMA loads with SGPR base + 32-bit VGPR offset, 16 fewer 64-bit VALU adds per iteration each
# baseline (speedup 1.0000x reference)
; #define PG8_STAGE(bufoff, gbase, voff) do { _Pragma("unroll") for (int _i = 0; _i < 2; ++_i) \
;         __builtin_amdgcn_global_load_lds((const unsigned*)((const char*)(gbase) + (voff)[_i]), (PG8_LAS unsigned*)(lds + (bufoff) + ldsw + _i * 8192), 16, 0, 0); } while (0)
; #define PG8_LDA(dst, b, h) do { _Pragma("unroll") for (int m = 0; m < 4; ++m) _Pragma("unroll") for (int k = 0; k < 2; ++k) dst[m][k] = *(const PG8_LAS bf16x8*)(lds + PG8_SA(b, h) + aoff + m * 2048 + k * 1024); } while (0)
; #define PG8_LDB(dst, b, h) do { _Pragma("unroll") for (int n = 0; n < 2; ++n) _Pragma("unroll") for (int k = 0; k < 2; ++k) dst[n][k] = *(const PG8_LAS bf16x8*)(lds + PG8_SB(b, h) + boff + n * 2048 + k * 1024); } while (0)
; #define PG8_MMA(ai, bj, At, Bt) do { __builtin_amdgcn_s_setprio(1); _Pragma("unroll") for (int m = 0; m < 4; ++m) _Pragma("unroll") for (int n = 0; n < 2; ++n) _Pragma("unroll") for (int k = 0; k < 2; ++k) \
;         acc[ai][bj][m][n] = __builtin_amdgcn_mfma_f32_16x16x32_bf16(Bt[n][k], At[m][k], acc[ai][bj][m][n], 0, 0, 0); __builtin_amdgcn_s_setprio(0); } while (0)
; #define PG8_WAIT_V(n) asm volatile("s_waitcnt vmcnt(" #n ")" ::: "memory")
; #define PG8_WAIT_L(n) asm volatile("s_waitcnt lgkmcnt(" #n ")" ::: "memory")
; template <class Epi, class Sched, bool ALIGN_EPI = false, bool SP2 = false>
; __device__ __forceinline__ void gemm_phase(PG8_LAS unsigned char* lds, const Gemm g, const Sched& S, const Epi& E) {
;     ...
;             const bool last = (t == nt - 2);
;             const char* a1 = cA + (size_t)(t + 1) * kstep;
;             const char* a2 = last ? nA : cA + (size_t)(t + 2) * kstep; const char* b2 = last ? nB : cB + (size_t)(t + 2) * kstep;
;             const char* a3 = a2 + kstep; const char* b3 = b2 + kstep;
;             if (last && has_next) S.a_ready(nxt);
;             if constexpr (SP2) {
;             PG8_LDB(B0, 0, 0); PG8_LDB(B1, 0, 1); PG8_SCHED; PG8_LDA(At, 0, 0); PG8_STAGE(PG8_SA(1, 1), a1 + hstep, voffA);
;             PG8_WAIT_V(8); PG8_WAIT_L(0); PG8_BAR; PG8_MMA(0, 0, At, B0); PG8_MMA(0, 1, At, B1); PG8_BAR; PG8_SCHED;
;             PG8_LDA(At, 0, 1); PG8_STAGE(PG8_SB(0, 0), b2, voffB); PG8_STAGE(PG8_SB(0, 1), b2 + hstep, voffB); PG8_STAGE(PG8_SA(0, 0), a2, voffA);
;             PG8_WAIT_V(8); PG8_WAIT_L(0); PG8_BAR; PG8_MMA(1, 0, At, B0); PG8_MMA(1, 1, At, B1); PG8_BAR; PG8_SCHED;
.LBB0_458:
	ds_read_b128 v[140:143], v149
	ds_read_b128 v[152:155], v149 offset:1024
	ds_read_b128 v[156:159], v149 offset:2048
	ds_read_b128 v[160:163], v149 offset:3072
	ds_read_b128 v[164:167], v150
	ds_read_b128 v[168:171], v150 offset:1024
	ds_read_b128 v[172:175], v150 offset:2048
	ds_read_b128 v[176:179], v150 offset:3072
	s_add_u32 s28, s26, 0xfff80080
	s_addc_u32 s29, s27, -1
	s_cmp_eq_u32 s49, 28
	s_cselect_b32 s35, s19, s29
	s_cselect_b32 s34, s31, s28
	s_cselect_b32 s29, s17, s48
	s_cselect_b32 s28, s46, s47
	s_add_i32 m0, s25, 0xc000
	ds_read_b128 v[180:183], v151
	ds_read_b128 v[184:187], v151 offset:1024
	ds_read_b128 v[188:191], v151 offset:2048
	ds_read_b128 v[192:195], v151 offset:3072
	ds_read_b128 v[196:199], v151 offset:4096
	ds_read_b128 v[200:203], v151 offset:5120
	ds_read_b128 v[204:207], v151 offset:6144
	ds_read_b128 v[208:211], v151 offset:7168
	global_load_lds_dwordx4 v132, s[26:27]
	s_add_i32 m0, s25, 0xe000
	s_nop 0
	global_load_lds_dwordx4 v134, s[26:27]
	s_waitcnt vmcnt(8)
	s_waitcnt lgkmcnt(0)
	s_barrier
	s_setprio 1
	s_waitcnt lgkmcnt(0)
	v_mfma_f32_16x16x32_bf16 v[124:127], v[140:143], v[180:183], v[124:127]
	v_mfma_f32_16x16x32_bf16 v[124:127], v[152:155], v[184:187], v[124:127]
	v_mfma_f32_16x16x32_bf16 v[116:119], v[152:155], v[192:195], v[116:119]
	v_mfma_f32_16x16x32_bf16 v[116:119], v[140:143], v[188:191], v[116:119]
	v_mfma_f32_16x16x32_bf16 v[108:111], v[140:143], v[196:199], v[108:111]
	v_mfma_f32_16x16x32_bf16 v[108:111], v[152:155], v[200:203], v[108:111]
	v_mfma_f32_16x16x32_bf16 v[92:95], v[152:155], v[208:211], v[92:95]
	v_mfma_f32_16x16x32_bf16 v[92:95], v[140:143], v[204:207], v[92:95]
	v_mfma_f32_16x16x32_bf16 v[80:83], v[156:159], v[204:207], v[80:83]
	v_mfma_f32_16x16x32_bf16 v[80:83], v[160:163], v[208:211], v[80:83]
	v_mfma_f32_16x16x32_bf16 v[100:103], v[160:163], v[200:203], v[100:103]
	v_mfma_f32_16x16x32_bf16 v[100:103], v[156:159], v[196:199], v[100:103]
	v_mfma_f32_16x16x32_bf16 v[112:115], v[156:159], v[188:191], v[112:115]
	v_mfma_f32_16x16x32_bf16 v[112:115], v[160:163], v[192:195], v[112:115]
	v_mfma_f32_16x16x32_bf16 v[120:123], v[160:163], v[184:187], v[120:123]
	v_mfma_f32_16x16x32_bf16 v[120:123], v[156:159], v[180:183], v[120:123]
	s_setprio 0
	s_setprio 1
	v_mfma_f32_16x16x32_bf16 v[104:107], v[164:167], v[180:183], v[104:107]
	v_mfma_f32_16x16x32_bf16 v[104:107], v[168:171], v[184:187], v[104:107]
	v_mfma_f32_16x16x32_bf16 v[88:91], v[168:171], v[192:195], v[88:91]
	v_mfma_f32_16x16x32_bf16 v[88:91], v[164:167], v[188:191], v[88:91]
	v_mfma_f32_16x16x32_bf16 v[76:79], v[164:167], v[196:199], v[76:79]
	v_mfma_f32_16x16x32_bf16 v[76:79], v[168:171], v[200:203], v[76:79]
	v_mfma_f32_16x16x32_bf16 v[68:71], v[168:171], v[208:211], v[68:71]
	v_mfma_f32_16x16x32_bf16 v[68:71], v[164:167], v[204:207], v[68:71]
	v_mfma_f32_16x16x32_bf16 v[64:67], v[172:175], v[204:207], v[64:67]
	v_mfma_f32_16x16x32_bf16 v[64:67], v[176:179], v[208:211], v[64:67]
	v_mfma_f32_16x16x32_bf16 v[72:75], v[176:179], v[200:203], v[72:75]
	v_mfma_f32_16x16x32_bf16 v[72:75], v[172:175], v[196:199], v[72:75]
	v_mfma_f32_16x16x32_bf16 v[84:87], v[172:175], v[188:191], v[84:87]
	v_mfma_f32_16x16x32_bf16 v[84:87], v[176:179], v[192:195], v[84:87]
	v_mfma_f32_16x16x32_bf16 v[96:99], v[176:179], v[184:187], v[96:99]
	v_mfma_f32_16x16x32_bf16 v[96:99], v[172:175], v[180:183], v[96:99]
	s_setprio 0
	s_barrier
	s_add_i32 s50, s43, s30
	s_mov_b32 m0, s50
	ds_read_b128 v[180:183], v151 offset:16384
	ds_read_b128 v[184:187], v151 offset:17408
	ds_read_b128 v[188:191], v151 offset:18432
	ds_read_b128 v[192:195], v151 offset:19456
	ds_read_b128 v[196:199], v151 offset:20480
	ds_read_b128 v[200:203], v151 offset:21504
	ds_read_b128 v[204:207], v151 offset:22528
	ds_read_b128 v[208:211], v151 offset:23552
	global_load_lds_dwordx4 v128, s[28:29]
	s_add_i32 m0, s50, 0x2000
	s_add_u32 s50, s28, 0x80000
	s_addc_u32 s51, s29, 0
	s_add_i32 s52, s44, s30
	global_load_lds_dwordx4 v130, s[28:29]
	s_mov_b32 m0, s52
	s_nop 0
	global_load_lds_dwordx4 v128, s[50:51]
	s_add_i32 m0, s52, 0x2000
	s_nop 0
	global_load_lds_dwordx4 v130, s[50:51]
	s_mov_b32 m0, s25
	s_nop 0
	global_load_lds_dwordx4 v128, s[34:35]
	s_mov_b32 m0, s36
	s_nop 0
	global_load_lds_dwordx4 v130, s[34:35]
	s_waitcnt vmcnt(8)
	s_waitcnt lgkmcnt(0)
	s_barrier
	s_setprio 1
	s_waitcnt lgkmcnt(0)
	v_mfma_f32_16x16x32_bf16 v[60:63], v[140:143], v[180:183], v[60:63]
	v_mfma_f32_16x16x32_bf16 v[60:63], v[152:155], v[184:187], v[60:63]
	v_mfma_f32_16x16x32_bf16 v[52:55], v[152:155], v[192:195], v[52:55]
	v_mfma_f32_16x16x32_bf16 v[52:55], v[140:143], v[188:191], v[52:55]
	v_mfma_f32_16x16x32_bf16 v[44:47], v[140:143], v[196:199], v[44:47]
	v_mfma_f32_16x16x32_bf16 v[44:47], v[152:155], v[200:203], v[44:47]
	v_mfma_f32_16x16x32_bf16 v[28:31], v[152:155], v[208:211], v[28:31]
	v_mfma_f32_16x16x32_bf16 v[28:31], v[140:143], v[204:207], v[28:31]
	v_mfma_f32_16x16x32_bf16 v[16:19], v[156:159], v[204:207], v[16:19]
	v_mfma_f32_16x16x32_bf16 v[16:19], v[160:163], v[208:211], v[16:19]
	v_mfma_f32_16x16x32_bf16 v[36:39], v[160:163], v[200:203], v[36:39]
	v_mfma_f32_16x16x32_bf16 v[36:39], v[156:159], v[196:199], v[36:39]
	v_mfma_f32_16x16x32_bf16 v[48:51], v[156:159], v[188:191], v[48:51]
	v_mfma_f32_16x16x32_bf16 v[48:51], v[160:163], v[192:195], v[48:51]
	v_mfma_f32_16x16x32_bf16 v[56:59], v[160:163], v[184:187], v[56:59]
	v_mfma_f32_16x16x32_bf16 v[56:59], v[156:159], v[180:183], v[56:59]
	s_setprio 0
	s_setprio 1
	v_mfma_f32_16x16x32_bf16 v[40:43], v[164:167], v[180:183], v[40:43]
	v_mfma_f32_16x16x32_bf16 v[40:43], v[168:171], v[184:187], v[40:43]
	v_mfma_f32_16x16x32_bf16 v[24:27], v[168:171], v[192:195], v[24:27]
	v_mfma_f32_16x16x32_bf16 v[24:27], v[164:167], v[188:191], v[24:27]
	v_mfma_f32_16x16x32_bf16 v[12:15], v[164:167], v[196:199], v[12:15]
	v_mfma_f32_16x16x32_bf16 v[12:15], v[168:171], v[200:203], v[12:15]
	v_mfma_f32_16x16x32_bf16 v[4:7], v[168:171], v[208:211], v[4:7]
	v_mfma_f32_16x16x32_bf16 v[4:7], v[164:167], v[204:207], v[4:7]
	v_mfma_f32_16x16x32_bf16 v[0:3], v[172:175], v[204:207], v[0:3]
	v_mfma_f32_16x16x32_bf16 v[0:3], v[176:179], v[208:211], v[0:3]
	v_mfma_f32_16x16x32_bf16 v[8:11], v[176:179], v[200:203], v[8:11]
	v_mfma_f32_16x16x32_bf16 v[8:11], v[172:175], v[196:199], v[8:11]
	v_mfma_f32_16x16x32_bf16 v[20:23], v[172:175], v[188:191], v[20:23]
	v_mfma_f32_16x16x32_bf16 v[20:23], v[176:179], v[192:195], v[20:23]
	v_mfma_f32_16x16x32_bf16 v[32:35], v[176:179], v[184:187], v[32:35]
	v_mfma_f32_16x16x32_bf16 v[32:35], v[172:175], v[180:183], v[32:35]
	s_setprio 0
	s_barrier
; #define PG8_STAGE(bufoff, gbase, voff) do { _Pragma("unroll") for (int _i = 0; _i < 2; ++_i) \
;         __builtin_amdgcn_global_load_lds((const unsigned*)((const char*)(gbase) + (voff)[_i]), (PG8_LAS unsigned*)(lds + (bufoff) + ldsw + _i * 8192), 16, 0, 0); } while (0)
; #define PG8_LDA(dst, b, h) do { _Pragma("unroll") for (int m = 0; m < 4; ++m) _Pragma("unroll") for (int k = 0; k < 2; ++k) dst[m][k] = *(const PG8_LAS bf16x8*)(lds + PG8_SA(b, h) + aoff + m * 2048 + k * 1024); } while (0)
; #define PG8_LDB(dst, b, h) do { _Pragma("unroll") for (int n = 0; n < 2; ++n) _Pragma("unroll") for (int k = 0; k < 2; ++k) dst[n][k] = *(const PG8_LAS bf16x8*)(lds + PG8_SB(b, h) + boff + n * 2048 + k * 1024); } while (0)
; #define PG8_MMA(ai, bj, At, Bt) do { __builtin_amdgcn_s_setprio(1); _Pragma("unroll") for (int m = 0; m < 4; ++m) _Pragma("unroll") for (int n = 0; n < 2; ++n) _Pragma("unroll") for (int k = 0; k < 2; ++k) \
;         acc[ai][bj][m][n] = __builtin_amdgcn_mfma_f32_16x16x32_bf16(Bt[n][k], At[m][k], acc[ai][bj][m][n], 0, 0, 0); __builtin_amdgcn_s_setprio(0); } while (0)
; #define PG8_WAIT_V(n) asm volatile("s_waitcnt vmcnt(" #n ")" ::: "memory")
; #define PG8_WAIT_L(n) asm volatile("s_waitcnt lgkmcnt(" #n ")" ::: "memory")
; #define PG8_BAR __builtin_amdgcn_s_barrier()
; #define PG8_SCHED __builtin_amdgcn_sched_barrier(0)
; template <class Epi, class Sched, bool ALIGN_EPI = false, bool SP2 = false>
; __device__ __forceinline__ void gemm_phase(PG8_LAS unsigned char* lds, const Gemm g, const Sched& S, const Epi& E) {
;     ...
;             PG8_LDB(B0, 1, 0); PG8_LDB(B1, 1, 1); PG8_SCHED; PG8_LDA(At, 1, 0); PG8_STAGE(PG8_SA(0, 1), a2 + hstep, voffA);
;             PG8_WAIT_V(8); PG8_WAIT_L(0); PG8_BAR; PG8_MMA(0, 0, At, B0); PG8_MMA(0, 1, At, B1); PG8_BAR; PG8_SCHED;
;             PG8_LDA(At, 1, 1); PG8_STAGE(PG8_SB(1, 0), b3, voffB); PG8_STAGE(PG8_SB(1, 1), b3 + hstep, voffB); PG8_STAGE(PG8_SA(1, 0), a3, voffA);
;             PG8_WAIT_V(8); PG8_WAIT_L(0); PG8_BAR; PG8_MMA(1, 0, At, B0); PG8_MMA(1, 1, At, B1); PG8_BAR; PG8_SCHED;
	s_add_i32 s50, 0, 0x18000
	s_add_i32 s51, 0, 0x1c000
	v_add_u32_e32 v160, s50, v147
	v_add_u32_e32 v176, s51, v147
	ds_read_b128 v[140:143], v160
	ds_read_b128 v[152:155], v160 offset:1024
	ds_read_b128 v[156:159], v160 offset:2048
	ds_read_b128 v[160:163], v160 offset:3072
	ds_read_b128 v[164:167], v176
	ds_read_b128 v[168:171], v176 offset:1024
	ds_read_b128 v[172:175], v176 offset:2048
	ds_read_b128 v[176:179], v176 offset:3072
	s_add_u32 s34, s34, 0x80000
	s_addc_u32 s35, s35, 0
	s_add_u32 s64, s34, 0xfff80080
	s_addc_u32 s65, s35, -1
	s_mov_b32 m0, s37
	ds_read_b128 v[180:183], v151 offset:32768
	ds_read_b128 v[184:187], v151 offset:33792
	ds_read_b128 v[188:191], v151 offset:34816
	ds_read_b128 v[192:195], v151 offset:35840
	ds_read_b128 v[196:199], v151 offset:36864
	ds_read_b128 v[200:203], v151 offset:37888
	ds_read_b128 v[204:207], v151 offset:38912
	ds_read_b128 v[208:211], v151 offset:39936
	global_load_lds_dwordx4 v128, s[34:35]
	s_mov_b32 m0, s38
	s_nop 0
	global_load_lds_dwordx4 v130, s[34:35]
	s_waitcnt vmcnt(8)
	s_waitcnt lgkmcnt(0)
	s_barrier
	s_setprio 1
	s_waitcnt lgkmcnt(0)
	v_mfma_f32_16x16x32_bf16 v[124:127], v[140:143], v[180:183], v[124:127]
	v_mfma_f32_16x16x32_bf16 v[124:127], v[152:155], v[184:187], v[124:127]
	v_mfma_f32_16x16x32_bf16 v[116:119], v[152:155], v[192:195], v[116:119]
	v_mfma_f32_16x16x32_bf16 v[116:119], v[140:143], v[188:191], v[116:119]
	v_mfma_f32_16x16x32_bf16 v[108:111], v[140:143], v[196:199], v[108:111]
	v_mfma_f32_16x16x32_bf16 v[108:111], v[152:155], v[200:203], v[108:111]
	v_mfma_f32_16x16x32_bf16 v[92:95], v[152:155], v[208:211], v[92:95]
	v_mfma_f32_16x16x32_bf16 v[92:95], v[140:143], v[204:207], v[92:95]
	v_mfma_f32_16x16x32_bf16 v[80:83], v[156:159], v[204:207], v[80:83]
	v_mfma_f32_16x16x32_bf16 v[80:83], v[160:163], v[208:211], v[80:83]
	v_mfma_f32_16x16x32_bf16 v[100:103], v[160:163], v[200:203], v[100:103]
	v_mfma_f32_16x16x32_bf16 v[100:103], v[156:159], v[196:199], v[100:103]
	v_mfma_f32_16x16x32_bf16 v[112:115], v[156:159], v[188:191], v[112:115]
	v_mfma_f32_16x16x32_bf16 v[112:115], v[160:163], v[192:195], v[112:115]
	v_mfma_f32_16x16x32_bf16 v[120:123], v[160:163], v[184:187], v[120:123]
	v_mfma_f32_16x16x32_bf16 v[120:123], v[156:159], v[180:183], v[120:123]
	s_setprio 0
	s_setprio 1
	v_mfma_f32_16x16x32_bf16 v[104:107], v[164:167], v[180:183], v[104:107]
	v_mfma_f32_16x16x32_bf16 v[104:107], v[168:171], v[184:187], v[104:107]
	v_mfma_f32_16x16x32_bf16 v[88:91], v[168:171], v[192:195], v[88:91]
	v_mfma_f32_16x16x32_bf16 v[88:91], v[164:167], v[188:191], v[88:91]
	v_mfma_f32_16x16x32_bf16 v[76:79], v[164:167], v[196:199], v[76:79]
	v_mfma_f32_16x16x32_bf16 v[76:79], v[168:171], v[200:203], v[76:79]
	v_mfma_f32_16x16x32_bf16 v[68:71], v[168:171], v[208:211], v[68:71]
	v_mfma_f32_16x16x32_bf16 v[68:71], v[164:167], v[204:207], v[68:71]
	v_mfma_f32_16x16x32_bf16 v[64:67], v[172:175], v[204:207], v[64:67]
	v_mfma_f32_16x16x32_bf16 v[64:67], v[176:179], v[208:211], v[64:67]
	v_mfma_f32_16x16x32_bf16 v[72:75], v[176:179], v[200:203], v[72:75]
	v_mfma_f32_16x16x32_bf16 v[72:75], v[172:175], v[196:199], v[72:75]
	v_mfma_f32_16x16x32_bf16 v[84:87], v[172:175], v[188:191], v[84:87]
	v_mfma_f32_16x16x32_bf16 v[84:87], v[176:179], v[192:195], v[84:87]
	v_mfma_f32_16x16x32_bf16 v[96:99], v[176:179], v[184:187], v[96:99]
	v_mfma_f32_16x16x32_bf16 v[96:99], v[172:175], v[180:183], v[96:99]
	s_setprio 0
	s_barrier
	s_add_i32 s34, s50, s30
	s_add_u32 s28, s28, 0x80
	s_addc_u32 s29, s29, 0
	s_mov_b32 m0, s34
	ds_read_b128 v[180:183], v151 offset:49152
	ds_read_b128 v[184:187], v151 offset:50176
	ds_read_b128 v[188:191], v151 offset:51200
	ds_read_b128 v[192:195], v151 offset:52224
	ds_read_b128 v[196:199], v151 offset:53248
	ds_read_b128 v[200:203], v151 offset:54272
	ds_read_b128 v[204:207], v151 offset:55296
	ds_read_b128 v[208:211], v151 offset:56320
	global_load_lds_dwordx4 v128, s[28:29]
	s_add_i32 m0, s34, 0x2000
	s_add_i32 s34, s51, s30
	global_load_lds_dwordx4 v130, s[28:29]
	s_add_u32 s28, s28, 0x80000
	s_addc_u32 s29, s29, 0
	s_mov_b32 m0, s34
	s_nop 0
	global_load_lds_dwordx4 v128, s[28:29]
	s_add_i32 m0, s34, 0x2000
	s_nop 0
	global_load_lds_dwordx4 v130, s[28:29]
	s_mov_b32 m0, s41
	s_nop 0
	global_load_lds_dwordx4 v128, s[64:65]
	s_mov_b32 m0, s42
	s_nop 0
	global_load_lds_dwordx4 v130, s[64:65]
	s_waitcnt vmcnt(8)
	s_waitcnt lgkmcnt(0)
	s_barrier
	s_setprio 1
	s_waitcnt lgkmcnt(0)
	v_mfma_f32_16x16x32_bf16 v[60:63], v[140:143], v[180:183], v[60:63]
	v_mfma_f32_16x16x32_bf16 v[60:63], v[152:155], v[184:187], v[60:63]
	v_mfma_f32_16x16x32_bf16 v[52:55], v[152:155], v[192:195], v[52:55]
	v_mfma_f32_16x16x32_bf16 v[52:55], v[140:143], v[188:191], v[52:55]
	v_mfma_f32_16x16x32_bf16 v[44:47], v[140:143], v[196:199], v[44:47]
	v_mfma_f32_16x16x32_bf16 v[44:47], v[152:155], v[200:203], v[44:47]
	v_mfma_f32_16x16x32_bf16 v[28:31], v[152:155], v[208:211], v[28:31]
	v_mfma_f32_16x16x32_bf16 v[28:31], v[140:143], v[204:207], v[28:31]
	v_mfma_f32_16x16x32_bf16 v[16:19], v[156:159], v[204:207], v[16:19]
	v_mfma_f32_16x16x32_bf16 v[16:19], v[160:163], v[208:211], v[16:19]
	v_mfma_f32_16x16x32_bf16 v[36:39], v[160:163], v[200:203], v[36:39]
	v_mfma_f32_16x16x32_bf16 v[36:39], v[156:159], v[196:199], v[36:39]
	v_mfma_f32_16x16x32_bf16 v[48:51], v[156:159], v[188:191], v[48:51]
	v_mfma_f32_16x16x32_bf16 v[48:51], v[160:163], v[192:195], v[48:51]
	v_mfma_f32_16x16x32_bf16 v[56:59], v[160:163], v[184:187], v[56:59]
	v_mfma_f32_16x16x32_bf16 v[56:59], v[156:159], v[180:183], v[56:59]
	s_setprio 0
	s_setprio 1
	v_mfma_f32_16x16x32_bf16 v[40:43], v[164:167], v[180:183], v[40:43]
	v_mfma_f32_16x16x32_bf16 v[40:43], v[168:171], v[184:187], v[40:43]
	v_mfma_f32_16x16x32_bf16 v[24:27], v[168:171], v[192:195], v[24:27]
	v_mfma_f32_16x16x32_bf16 v[24:27], v[164:167], v[188:191], v[24:27]
	v_mfma_f32_16x16x32_bf16 v[12:15], v[164:167], v[196:199], v[12:15]
	v_mfma_f32_16x16x32_bf16 v[12:15], v[168:171], v[200:203], v[12:15]
	v_mfma_f32_16x16x32_bf16 v[4:7], v[168:171], v[208:211], v[4:7]
	v_mfma_f32_16x16x32_bf16 v[4:7], v[164:167], v[204:207], v[4:7]
	v_mfma_f32_16x16x32_bf16 v[0:3], v[172:175], v[204:207], v[0:3]
	v_mfma_f32_16x16x32_bf16 v[0:3], v[176:179], v[208:211], v[0:3]
	v_mfma_f32_16x16x32_bf16 v[8:11], v[176:179], v[200:203], v[8:11]
	v_mfma_f32_16x16x32_bf16 v[8:11], v[172:175], v[196:199], v[8:11]
	v_mfma_f32_16x16x32_bf16 v[20:23], v[172:175], v[188:191], v[20:23]
	v_mfma_f32_16x16x32_bf16 v[20:23], v[176:179], v[192:195], v[20:23]
	v_mfma_f32_16x16x32_bf16 v[32:35], v[176:179], v[184:187], v[32:35]
	v_mfma_f32_16x16x32_bf16 v[32:35], v[172:175], v[180:183], v[32:35]
	s_setprio 0
	s_barrier
	s_add_i32 s49, s49, 2
	s_add_u32 s26, s26, 0x100
	s_addc_u32 s27, s27, 0
	s_add_u32 s47, s47, 0x100
	s_addc_u32 s48, s48, 0
	s_cmp_gt_u32 s49, 29
	s_cbranch_scc0 .LBB0_458

; #define PG8_STAGE(bufoff, gbase, voff) do { _Pragma("unroll") for (int _i = 0; _i < 2; ++_i) \
;         __builtin_amdgcn_global_load_lds((const unsigned*)((const char*)(gbase) + (voff)[_i]), (PG8_LAS unsigned*)(lds + (bufoff) + ldsw + _i * 8192), 16, 0, 0); } while (0)
; #define PG8_LDA(dst, b, h) do { _Pragma("unroll") for (int m = 0; m < 4; ++m) _Pragma("unroll") for (int k = 0; k < 2; ++k) dst[m][k] = *(const PG8_LAS bf16x8*)(lds + PG8_SA(b, h) + aoff + m * 2048 + k * 1024); } while (0)
; #define PG8_LDB(dst, b, h) do { _Pragma("unroll") for (int n = 0; n < 2; ++n) _Pragma("unroll") for (int k = 0; k < 2; ++k) dst[n][k] = *(const PG8_LAS bf16x8*)(lds + PG8_SB(b, h) + boff + n * 2048 + k * 1024); } while (0)
; #define PG8_SCHED __builtin_amdgcn_sched_barrier(0)
; template <class Epi, class Sched, bool ALIGN_EPI = false, bool SP2 = false>
; __device__ __forceinline__ void gemm_phase(PG8_LAS unsigned char* lds, const Gemm g, const Sched& S, const Epi& E) {
;     ...
;             const bool last = (t == nt - 2);
;             const char* a1 = cA + (size_t)(t + 1) * kstep;
;             const char* a2 = last ? nA : cA + (size_t)(t + 2) * kstep; const char* b2 = last ? nB : cB + (size_t)(t + 2) * kstep;
;             const char* a3 = a2 + kstep; const char* b3 = b2 + kstep;
;             if (last && has_next) S.a_ready(nxt);
;             if constexpr (SP2) {
;             PG8_LDB(B0, 0, 0); PG8_LDB(B1, 0, 1); PG8_SCHED; PG8_LDA(At, 0, 0); PG8_STAGE(PG8_SA(1, 1), a1 + hstep, voffA);
.Lp3_k2:
	ds_read_b128 v[140:143], v149
	ds_read_b128 v[152:155], v149 offset:1024
	ds_read_b128 v[156:159], v149 offset:2048
	ds_read_b128 v[160:163], v149 offset:3072
	ds_read_b128 v[164:167], v150
	ds_read_b128 v[168:171], v150 offset:1024
	ds_read_b128 v[172:175], v150 offset:2048
	ds_read_b128 v[176:179], v150 offset:3072
	s_add_u32 s28, s26, 0xfff80080
	s_addc_u32 s29, s27, -1
	s_cmp_eq_u32 s49, 28
	s_cselect_b32 s35, s19, s29
	s_cselect_b32 s34, s31, s28
	s_cselect_b32 s29, s17, s48
	s_cselect_b32 s28, s46, s47
	s_add_i32 m0, s25, 0xc000
	ds_read_b128 v[180:183], v151
	ds_read_b128 v[184:187], v151 offset:1024
	ds_read_b128 v[188:191], v151 offset:2048
	ds_read_b128 v[192:195], v151 offset:3072
	ds_read_b128 v[196:199], v151 offset:4096
	ds_read_b128 v[200:203], v151 offset:5120
	ds_read_b128 v[204:207], v151 offset:6144
	ds_read_b128 v[208:211], v151 offset:7168
	global_load_lds_dwordx4 v132, s[26:27]
	s_add_i32 m0, s25, 0xe000
	s_nop 0
	global_load_lds_dwordx4 v134, s[26:27]
	s_waitcnt vmcnt(8)
	s_add_i32 s86, s49, 2
	s_cmp_ge_u32 s86, 16
	s_cbranch_scc1 .Lsbt_8_16
	s_cmp_ge_u32 s86, 8
	s_cbranch_scc1 .Lsbt_4_8
	s_cmp_ge_u32 s86, 4
	s_cbranch_scc1 .Lsbt_2_4
	s_cmp_ge_u32 s86, 2
	s_cbranch_scc1 .Lsbt_1_2
	s_branch .Lsb_0

; #define PG8_STAGE(bufoff, gbase, voff) do { _Pragma("unroll") for (int _i = 0; _i < 2; ++_i) \
;         __builtin_amdgcn_global_load_lds((const unsigned*)((const char*)(gbase) + (voff)[_i]), (PG8_LAS unsigned*)(lds + (bufoff) + ldsw + _i * 8192), 16, 0, 0); } while (0)
; #define PG8_LDA(dst, b, h) do { _Pragma("unroll") for (int m = 0; m < 4; ++m) _Pragma("unroll") for (int k = 0; k < 2; ++k) dst[m][k] = *(const PG8_LAS bf16x8*)(lds + PG8_SA(b, h) + aoff + m * 2048 + k * 1024); } while (0)
; #define PG8_MMA(ai, bj, At, Bt) do { __builtin_amdgcn_s_setprio(1); _Pragma("unroll") for (int m = 0; m < 4; ++m) _Pragma("unroll") for (int n = 0; n < 2; ++n) _Pragma("unroll") for (int k = 0; k < 2; ++k) \
;         acc[ai][bj][m][n] = __builtin_amdgcn_mfma_f32_16x16x32_bf16(Bt[n][k], At[m][k], acc[ai][bj][m][n], 0, 0, 0); __builtin_amdgcn_s_setprio(0); } while (0)
; #define PG8_WAIT_V(n) asm volatile("s_waitcnt vmcnt(" #n ")" ::: "memory")
; #define PG8_WAIT_L(n) asm volatile("s_waitcnt lgkmcnt(" #n ")" ::: "memory")
; #define PG8_BAR __builtin_amdgcn_s_barrier()
; #define PG8_SCHED __builtin_amdgcn_sched_barrier(0)
; template <class Epi, class Sched, bool ALIGN_EPI = false, bool SP2 = false>
; __device__ __forceinline__ void gemm_phase(PG8_LAS unsigned char* lds, const Gemm g, const Sched& S, const Epi& E) {
;     ...
;             PG8_WAIT_V(8); PG8_WAIT_L(0); PG8_BAR; PG8_MMA(0, 0, At, B0); PG8_MMA(0, 1, At, B1); PG8_BAR; PG8_SCHED;
;             PG8_LDA(At, 0, 1); PG8_STAGE(PG8_SB(0, 0), b2, voffB); PG8_STAGE(PG8_SB(0, 1), b2 + hstep, voffB); PG8_STAGE(PG8_SA(0, 0), a2, voffA);
;             PG8_WAIT_V(8); PG8_WAIT_L(0); PG8_BAR; PG8_MMA(1, 0, At, B0); PG8_MMA(1, 1, At, B1); PG8_BAR; PG8_SCHED;
.Lsb_ret:
	s_waitcnt lgkmcnt(0)
	s_barrier
	s_setprio 1
	s_waitcnt lgkmcnt(0)
	v_mfma_f32_16x16x32_bf16 v[124:127], v[140:143], v[180:183], v[124:127]
	v_mfma_f32_16x16x32_bf16 v[124:127], v[152:155], v[184:187], v[124:127]
	v_mfma_f32_16x16x32_bf16 v[116:119], v[152:155], v[192:195], v[116:119]
	v_mfma_f32_16x16x32_bf16 v[116:119], v[140:143], v[188:191], v[116:119]
	v_mfma_f32_16x16x32_bf16 v[108:111], v[140:143], v[196:199], v[108:111]
	v_mfma_f32_16x16x32_bf16 v[108:111], v[152:155], v[200:203], v[108:111]
	v_mfma_f32_16x16x32_bf16 v[92:95], v[152:155], v[208:211], v[92:95]
	v_mfma_f32_16x16x32_bf16 v[92:95], v[140:143], v[204:207], v[92:95]
	v_mfma_f32_16x16x32_bf16 v[80:83], v[156:159], v[204:207], v[80:83]
	v_mfma_f32_16x16x32_bf16 v[80:83], v[160:163], v[208:211], v[80:83]
	v_mfma_f32_16x16x32_bf16 v[100:103], v[160:163], v[200:203], v[100:103]
	v_mfma_f32_16x16x32_bf16 v[100:103], v[156:159], v[196:199], v[100:103]
	v_mfma_f32_16x16x32_bf16 v[112:115], v[156:159], v[188:191], v[112:115]
	v_mfma_f32_16x16x32_bf16 v[112:115], v[160:163], v[192:195], v[112:115]
	v_mfma_f32_16x16x32_bf16 v[120:123], v[160:163], v[184:187], v[120:123]
	v_mfma_f32_16x16x32_bf16 v[120:123], v[156:159], v[180:183], v[120:123]
	s_setprio 0
	s_setprio 1
	v_mfma_f32_16x16x32_bf16 v[104:107], v[164:167], v[180:183], v[104:107]
	v_mfma_f32_16x16x32_bf16 v[104:107], v[168:171], v[184:187], v[104:107]
	v_mfma_f32_16x16x32_bf16 v[88:91], v[168:171], v[192:195], v[88:91]
	v_mfma_f32_16x16x32_bf16 v[88:91], v[164:167], v[188:191], v[88:91]
	v_mfma_f32_16x16x32_bf16 v[76:79], v[164:167], v[196:199], v[76:79]
	v_mfma_f32_16x16x32_bf16 v[76:79], v[168:171], v[200:203], v[76:79]
	v_mfma_f32_16x16x32_bf16 v[68:71], v[168:171], v[208:211], v[68:71]
	v_mfma_f32_16x16x32_bf16 v[68:71], v[164:167], v[204:207], v[68:71]
	v_mfma_f32_16x16x32_bf16 v[64:67], v[172:175], v[204:207], v[64:67]
	v_mfma_f32_16x16x32_bf16 v[64:67], v[176:179], v[208:211], v[64:67]
	v_mfma_f32_16x16x32_bf16 v[72:75], v[176:179], v[200:203], v[72:75]
	v_mfma_f32_16x16x32_bf16 v[72:75], v[172:175], v[196:199], v[72:75]
	v_mfma_f32_16x16x32_bf16 v[84:87], v[172:175], v[188:191], v[84:87]
	v_mfma_f32_16x16x32_bf16 v[84:87], v[176:179], v[192:195], v[84:87]
	v_mfma_f32_16x16x32_bf16 v[96:99], v[176:179], v[184:187], v[96:99]
	v_mfma_f32_16x16x32_bf16 v[96:99], v[172:175], v[180:183], v[96:99]
	s_setprio 0
	s_barrier
	s_add_i32 s50, s43, s30
	s_mov_b32 m0, s50
	ds_read_b128 v[180:183], v151 offset:16384
	ds_read_b128 v[184:187], v151 offset:17408
	ds_read_b128 v[188:191], v151 offset:18432
	ds_read_b128 v[192:195], v151 offset:19456
	ds_read_b128 v[196:199], v151 offset:20480
	ds_read_b128 v[200:203], v151 offset:21504
	ds_read_b128 v[204:207], v151 offset:22528
	ds_read_b128 v[208:211], v151 offset:23552
	global_load_lds_dwordx4 v128, s[28:29]
	s_add_i32 m0, s50, 0x2000
	s_add_u32 s50, s28, 0x80000
	s_addc_u32 s51, s29, 0
	s_add_i32 s52, s44, s30
	global_load_lds_dwordx4 v130, s[28:29]
	s_mov_b32 m0, s52
	s_nop 0
	global_load_lds_dwordx4 v128, s[50:51]
	s_add_i32 m0, s52, 0x2000
	s_nop 0
	global_load_lds_dwordx4 v130, s[50:51]
	s_mov_b32 m0, s25
	s_nop 0
	global_load_lds_dwordx4 v128, s[34:35]
	s_mov_b32 m0, s36
	s_nop 0
	global_load_lds_dwordx4 v130, s[34:35]
	s_waitcnt vmcnt(10)
	s_waitcnt lgkmcnt(0)
	s_barrier
	s_setprio 1
	s_waitcnt lgkmcnt(0)
	v_mfma_f32_16x16x32_bf16 v[60:63], v[140:143], v[180:183], v[60:63]
	v_mfma_f32_16x16x32_bf16 v[60:63], v[152:155], v[184:187], v[60:63]
	v_mfma_f32_16x16x32_bf16 v[52:55], v[152:155], v[192:195], v[52:55]
	v_mfma_f32_16x16x32_bf16 v[52:55], v[140:143], v[188:191], v[52:55]
	v_mfma_f32_16x16x32_bf16 v[44:47], v[140:143], v[196:199], v[44:47]
	v_mfma_f32_16x16x32_bf16 v[44:47], v[152:155], v[200:203], v[44:47]
	v_mfma_f32_16x16x32_bf16 v[28:31], v[152:155], v[208:211], v[28:31]
	v_mfma_f32_16x16x32_bf16 v[28:31], v[140:143], v[204:207], v[28:31]
	v_mfma_f32_16x16x32_bf16 v[16:19], v[156:159], v[204:207], v[16:19]
	v_mfma_f32_16x16x32_bf16 v[16:19], v[160:163], v[208:211], v[16:19]
	v_mfma_f32_16x16x32_bf16 v[36:39], v[160:163], v[200:203], v[36:39]
	v_mfma_f32_16x16x32_bf16 v[36:39], v[156:159], v[196:199], v[36:39]
	v_mfma_f32_16x16x32_bf16 v[48:51], v[156:159], v[188:191], v[48:51]
	v_mfma_f32_16x16x32_bf16 v[48:51], v[160:163], v[192:195], v[48:51]
	v_mfma_f32_16x16x32_bf16 v[56:59], v[160:163], v[184:187], v[56:59]
	v_mfma_f32_16x16x32_bf16 v[56:59], v[156:159], v[180:183], v[56:59]
	s_setprio 0
	s_setprio 1
	v_mfma_f32_16x16x32_bf16 v[40:43], v[164:167], v[180:183], v[40:43]
	v_mfma_f32_16x16x32_bf16 v[40:43], v[168:171], v[184:187], v[40:43]
	v_mfma_f32_16x16x32_bf16 v[24:27], v[168:171], v[192:195], v[24:27]
	v_mfma_f32_16x16x32_bf16 v[24:27], v[164:167], v[188:191], v[24:27]
	v_mfma_f32_16x16x32_bf16 v[12:15], v[164:167], v[196:199], v[12:15]
	v_mfma_f32_16x16x32_bf16 v[12:15], v[168:171], v[200:203], v[12:15]
	v_mfma_f32_16x16x32_bf16 v[4:7], v[168:171], v[208:211], v[4:7]
	v_mfma_f32_16x16x32_bf16 v[4:7], v[164:167], v[204:207], v[4:7]
	v_mfma_f32_16x16x32_bf16 v[0:3], v[172:175], v[204:207], v[0:3]
	v_mfma_f32_16x16x32_bf16 v[0:3], v[176:179], v[208:211], v[0:3]
	v_mfma_f32_16x16x32_bf16 v[8:11], v[176:179], v[200:203], v[8:11]
	v_mfma_f32_16x16x32_bf16 v[8:11], v[172:175], v[196:199], v[8:11]
	v_mfma_f32_16x16x32_bf16 v[20:23], v[172:175], v[188:191], v[20:23]
	v_mfma_f32_16x16x32_bf16 v[20:23], v[176:179], v[192:195], v[20:23]
	v_mfma_f32_16x16x32_bf16 v[32:35], v[176:179], v[184:187], v[32:35]
	v_mfma_f32_16x16x32_bf16 v[32:35], v[172:175], v[180:183], v[32:35]
	s_setprio 0
	s_barrier
; #define PG8_STAGE(bufoff, gbase, voff) do { _Pragma("unroll") for (int _i = 0; _i < 2; ++_i) \
;         __builtin_amdgcn_global_load_lds((const unsigned*)((const char*)(gbase) + (voff)[_i]), (PG8_LAS unsigned*)(lds + (bufoff) + ldsw + _i * 8192), 16, 0, 0); } while (0)
; #define PG8_LDA(dst, b, h) do { _Pragma("unroll") for (int m = 0; m < 4; ++m) _Pragma("unroll") for (int k = 0; k < 2; ++k) dst[m][k] = *(const PG8_LAS bf16x8*)(lds + PG8_SA(b, h) + aoff + m * 2048 + k * 1024); } while (0)
; #define PG8_LDB(dst, b, h) do { _Pragma("unroll") for (int n = 0; n < 2; ++n) _Pragma("unroll") for (int k = 0; k < 2; ++k) dst[n][k] = *(const PG8_LAS bf16x8*)(lds + PG8_SB(b, h) + boff + n * 2048 + k * 1024); } while (0)
; #define PG8_MMA(ai, bj, At, Bt) do { __builtin_amdgcn_s_setprio(1); _Pragma("unroll") for (int m = 0; m < 4; ++m) _Pragma("unroll") for (int n = 0; n < 2; ++n) _Pragma("unroll") for (int k = 0; k < 2; ++k) \
;         acc[ai][bj][m][n] = __builtin_amdgcn_mfma_f32_16x16x32_bf16(Bt[n][k], At[m][k], acc[ai][bj][m][n], 0, 0, 0); __builtin_amdgcn_s_setprio(0); } while (0)
; #define PG8_WAIT_V(n) asm volatile("s_waitcnt vmcnt(" #n ")" ::: "memory")
; #define PG8_WAIT_L(n) asm volatile("s_waitcnt lgkmcnt(" #n ")" ::: "memory")
; #define PG8_BAR __builtin_amdgcn_s_barrier()
; #define PG8_SCHED __builtin_amdgcn_sched_barrier(0)
; template <class Epi, class Sched, bool ALIGN_EPI = false, bool SP2 = false>
; __device__ __forceinline__ void gemm_phase(PG8_LAS unsigned char* lds, const Gemm g, const Sched& S, const Epi& E) {
;     ...
;             PG8_LDB(B0, 1, 0); PG8_LDB(B1, 1, 1); PG8_SCHED; PG8_LDA(At, 1, 0); PG8_STAGE(PG8_SA(0, 1), a2 + hstep, voffA);
;             PG8_WAIT_V(8); PG8_WAIT_L(0); PG8_BAR; PG8_MMA(0, 0, At, B0); PG8_MMA(0, 1, At, B1); PG8_BAR; PG8_SCHED;
;             PG8_LDA(At, 1, 1); PG8_STAGE(PG8_SB(1, 0), b3, voffB); PG8_STAGE(PG8_SB(1, 1), b3 + hstep, voffB); PG8_STAGE(PG8_SA(1, 0), a3, voffA);
;             PG8_WAIT_V(8); PG8_WAIT_L(0); PG8_BAR; PG8_MMA(1, 0, At, B0); PG8_MMA(1, 1, At, B1); PG8_BAR; PG8_SCHED;
	s_add_i32 s50, 0, 0x18000
	s_add_i32 s51, 0, 0x1c000
	v_add_u32_e32 v160, s50, v147
	v_add_u32_e32 v176, s51, v147
	ds_read_b128 v[140:143], v160
	ds_read_b128 v[152:155], v160 offset:1024
	ds_read_b128 v[156:159], v160 offset:2048
	ds_read_b128 v[160:163], v160 offset:3072
	ds_read_b128 v[164:167], v176
	ds_read_b128 v[168:171], v176 offset:1024
	ds_read_b128 v[172:175], v176 offset:2048
	ds_read_b128 v[176:179], v176 offset:3072
	s_add_u32 s34, s34, 0x80000
	s_addc_u32 s35, s35, 0
	s_add_u32 s64, s34, 0xfff80080
	s_addc_u32 s65, s35, -1
	s_mov_b32 m0, s37
	ds_read_b128 v[180:183], v151 offset:32768
	ds_read_b128 v[184:187], v151 offset:33792
	ds_read_b128 v[188:191], v151 offset:34816
	ds_read_b128 v[192:195], v151 offset:35840
	ds_read_b128 v[196:199], v151 offset:36864
	ds_read_b128 v[200:203], v151 offset:37888
	ds_read_b128 v[204:207], v151 offset:38912
	ds_read_b128 v[208:211], v151 offset:39936
	global_load_lds_dwordx4 v128, s[34:35]
	s_mov_b32 m0, s38
	s_nop 0
	global_load_lds_dwordx4 v130, s[34:35]
	s_waitcnt vmcnt(10)
	s_waitcnt lgkmcnt(0)
	s_barrier
	s_setprio 1
	s_waitcnt lgkmcnt(0)
	v_mfma_f32_16x16x32_bf16 v[124:127], v[140:143], v[180:183], v[124:127]
	v_mfma_f32_16x16x32_bf16 v[124:127], v[152:155], v[184:187], v[124:127]
	v_mfma_f32_16x16x32_bf16 v[116:119], v[152:155], v[192:195], v[116:119]
	v_mfma_f32_16x16x32_bf16 v[116:119], v[140:143], v[188:191], v[116:119]
	v_mfma_f32_16x16x32_bf16 v[108:111], v[140:143], v[196:199], v[108:111]
	v_mfma_f32_16x16x32_bf16 v[108:111], v[152:155], v[200:203], v[108:111]
	v_mfma_f32_16x16x32_bf16 v[92:95], v[152:155], v[208:211], v[92:95]
	v_mfma_f32_16x16x32_bf16 v[92:95], v[140:143], v[204:207], v[92:95]
	v_mfma_f32_16x16x32_bf16 v[80:83], v[156:159], v[204:207], v[80:83]
	v_mfma_f32_16x16x32_bf16 v[80:83], v[160:163], v[208:211], v[80:83]
	v_mfma_f32_16x16x32_bf16 v[100:103], v[160:163], v[200:203], v[100:103]
	v_mfma_f32_16x16x32_bf16 v[100:103], v[156:159], v[196:199], v[100:103]
	v_mfma_f32_16x16x32_bf16 v[112:115], v[156:159], v[188:191], v[112:115]
	v_mfma_f32_16x16x32_bf16 v[112:115], v[160:163], v[192:195], v[112:115]
	v_mfma_f32_16x16x32_bf16 v[120:123], v[160:163], v[184:187], v[120:123]
	v_mfma_f32_16x16x32_bf16 v[120:123], v[156:159], v[180:183], v[120:123]
	s_setprio 0
	s_setprio 1
	v_mfma_f32_16x16x32_bf16 v[104:107], v[164:167], v[180:183], v[104:107]
	v_mfma_f32_16x16x32_bf16 v[104:107], v[168:171], v[184:187], v[104:107]
	v_mfma_f32_16x16x32_bf16 v[88:91], v[168:171], v[192:195], v[88:91]
	v_mfma_f32_16x16x32_bf16 v[88:91], v[164:167], v[188:191], v[88:91]
	v_mfma_f32_16x16x32_bf16 v[76:79], v[164:167], v[196:199], v[76:79]
	v_mfma_f32_16x16x32_bf16 v[76:79], v[168:171], v[200:203], v[76:79]
	v_mfma_f32_16x16x32_bf16 v[68:71], v[168:171], v[208:211], v[68:71]
	v_mfma_f32_16x16x32_bf16 v[68:71], v[164:167], v[204:207], v[68:71]
	v_mfma_f32_16x16x32_bf16 v[64:67], v[172:175], v[204:207], v[64:67]
	v_mfma_f32_16x16x32_bf16 v[64:67], v[176:179], v[208:211], v[64:67]
	v_mfma_f32_16x16x32_bf16 v[72:75], v[176:179], v[200:203], v[72:75]
	v_mfma_f32_16x16x32_bf16 v[72:75], v[172:175], v[196:199], v[72:75]
	v_mfma_f32_16x16x32_bf16 v[84:87], v[172:175], v[188:191], v[84:87]
	v_mfma_f32_16x16x32_bf16 v[84:87], v[176:179], v[192:195], v[84:87]
	v_mfma_f32_16x16x32_bf16 v[96:99], v[176:179], v[184:187], v[96:99]
	v_mfma_f32_16x16x32_bf16 v[96:99], v[172:175], v[180:183], v[96:99]
	s_setprio 0
	s_barrier
	s_add_i32 s34, s50, s30
	s_add_u32 s28, s28, 0x80
	s_addc_u32 s29, s29, 0
	s_mov_b32 m0, s34
	ds_read_b128 v[180:183], v151 offset:49152
	ds_read_b128 v[184:187], v151 offset:50176
	ds_read_b128 v[188:191], v151 offset:51200
	ds_read_b128 v[192:195], v151 offset:52224
	ds_read_b128 v[196:199], v151 offset:53248
	ds_read_b128 v[200:203], v151 offset:54272
	ds_read_b128 v[204:207], v151 offset:55296
	ds_read_b128 v[208:211], v151 offset:56320
	global_load_lds_dwordx4 v128, s[28:29]
	s_add_i32 m0, s34, 0x2000
	s_add_i32 s34, s51, s30
	global_load_lds_dwordx4 v130, s[28:29]
	s_add_u32 s28, s28, 0x80000
	s_addc_u32 s29, s29, 0
	s_mov_b32 m0, s34
	s_nop 0
	global_load_lds_dwordx4 v128, s[28:29]
	s_add_i32 m0, s34, 0x2000
	s_nop 0
	global_load_lds_dwordx4 v130, s[28:29]
	s_mov_b32 m0, s41
	s_nop 0
	global_load_lds_dwordx4 v128, s[64:65]
	s_mov_b32 m0, s42
	s_nop 0
	global_load_lds_dwordx4 v130, s[64:65]
	s_waitcnt vmcnt(8)
	s_waitcnt lgkmcnt(0)
	s_barrier
	s_setprio 1
	s_waitcnt lgkmcnt(0)
	v_mfma_f32_16x16x32_bf16 v[60:63], v[140:143], v[180:183], v[60:63]
	v_mfma_f32_16x16x32_bf16 v[60:63], v[152:155], v[184:187], v[60:63]
	v_mfma_f32_16x16x32_bf16 v[52:55], v[152:155], v[192:195], v[52:55]
	v_mfma_f32_16x16x32_bf16 v[52:55], v[140:143], v[188:191], v[52:55]
	v_mfma_f32_16x16x32_bf16 v[44:47], v[140:143], v[196:199], v[44:47]
	v_mfma_f32_16x16x32_bf16 v[44:47], v[152:155], v[200:203], v[44:47]
	v_mfma_f32_16x16x32_bf16 v[28:31], v[152:155], v[208:211], v[28:31]
	v_mfma_f32_16x16x32_bf16 v[28:31], v[140:143], v[204:207], v[28:31]
	v_mfma_f32_16x16x32_bf16 v[16:19], v[156:159], v[204:207], v[16:19]
	v_mfma_f32_16x16x32_bf16 v[16:19], v[160:163], v[208:211], v[16:19]
	v_mfma_f32_16x16x32_bf16 v[36:39], v[160:163], v[200:203], v[36:39]
	v_mfma_f32_16x16x32_bf16 v[36:39], v[156:159], v[196:199], v[36:39]
	v_mfma_f32_16x16x32_bf16 v[48:51], v[156:159], v[188:191], v[48:51]
	v_mfma_f32_16x16x32_bf16 v[48:51], v[160:163], v[192:195], v[48:51]
	v_mfma_f32_16x16x32_bf16 v[56:59], v[160:163], v[184:187], v[56:59]
	v_mfma_f32_16x16x32_bf16 v[56:59], v[156:159], v[180:183], v[56:59]
	s_setprio 0
	s_setprio 1
	v_mfma_f32_16x16x32_bf16 v[40:43], v[164:167], v[180:183], v[40:43]
	v_mfma_f32_16x16x32_bf16 v[40:43], v[168:171], v[184:187], v[40:43]
	v_mfma_f32_16x16x32_bf16 v[24:27], v[168:171], v[192:195], v[24:27]
	v_mfma_f32_16x16x32_bf16 v[24:27], v[164:167], v[188:191], v[24:27]
	v_mfma_f32_16x16x32_bf16 v[12:15], v[164:167], v[196:199], v[12:15]
	v_mfma_f32_16x16x32_bf16 v[12:15], v[168:171], v[200:203], v[12:15]
	v_mfma_f32_16x16x32_bf16 v[4:7], v[168:171], v[208:211], v[4:7]
	v_mfma_f32_16x16x32_bf16 v[4:7], v[164:167], v[204:207], v[4:7]
	v_mfma_f32_16x16x32_bf16 v[0:3], v[172:175], v[204:207], v[0:3]
	v_mfma_f32_16x16x32_bf16 v[0:3], v[176:179], v[208:211], v[0:3]
	v_mfma_f32_16x16x32_bf16 v[8:11], v[176:179], v[200:203], v[8:11]
	v_mfma_f32_16x16x32_bf16 v[8:11], v[172:175], v[196:199], v[8:11]
	v_mfma_f32_16x16x32_bf16 v[20:23], v[172:175], v[188:191], v[20:23]
	v_mfma_f32_16x16x32_bf16 v[20:23], v[176:179], v[192:195], v[20:23]
	v_mfma_f32_16x16x32_bf16 v[32:35], v[176:179], v[184:187], v[32:35]
	v_mfma_f32_16x16x32_bf16 v[32:35], v[172:175], v[180:183], v[32:35]
	s_setprio 0
	s_barrier
	s_add_i32 s49, s49, 2
	s_add_u32 s26, s26, 0x100
	s_addc_u32 s27, s27, 0
	s_add_u32 s47, s47, 0x100
	s_addc_u32 s48, s48, 0
	s_cmp_gt_u32 s49, 29
	s_cbranch_scc0 .Lp3_k2
	s_branch .Lp3_k2_exit
